# DF loops: a wave that flagged itself finished tests the stop flags before staging (stopping units leave no LDS-DMA in flight); landed-before-exchange waits kept
# speedup vs baseline: 1.0032x; 1.0032x over previous
.LBB0_385:
	s_and_b64 vcc, exec, s[2:3]
	s_cbranch_vccz .LBB0_300
	s_mov_b32 s29, 0
	s_lshr_b32 s2, s97, 4
	s_bfe_u32 s22, s97, 0x40001
	s_and_b32 s2, s2, 2
	s_and_b32 s3, s97, 1
	s_ashr_i32 s6, s97, 6
	s_xor_b32 s8, s22, 15
	s_or_b32 s2, s2, s3
	s_xor_b32 s16, s2, 2
	s_lshl_b32 s2, s8, 7
	v_readlane_b32 s3, v255, 29
	s_ashr_i32 s7, s6, 31
	s_or_b32 s9, s2, s3
	s_lshl_b32 s10, s16, 18
	s_lshl_b64 s[2:3], s[6:7], 21
	v_mov_b32_e32 v216, v231
	s_add_u32 s17, s78, s2
	s_addc_u32 s18, s79, s3
	v_and_b32_e32 v218, 31, v216
	s_lshl_b32 s2, s16, 19
	v_or_b32_e32 v179, s9, v218
	s_add_u32 s2, s17, s2
	s_addc_u32 s3, s18, 0
	v_lshlrev_b32_e32 v0, 8, v179
	v_ashrrev_i32_e32 v219, 5, v216
	v_lshl_add_u64 v[2:3], s[2:3], 0, v[0:1]
	s_mov_b32 s85, s81
	v_lshl_add_u64 v[4:5], v[2:3], 0, s[84:85]
	v_lshlrev_b32_e32 v2, 3, v219
	v_ashrrev_i32_e32 v3, 31, v2
	v_lshl_add_u64 v[4:5], v[2:3], 1, v[4:5]
	s_brev_b32 s2, 32
	v_add_co_u32_e32 v6, vcc, s2, v4
	s_mov_b64 s[2:3], 0x4000000
	s_nop 0
	v_addc_co_u32_e32 v7, vcc, 0, v5, vcc
	global_load_dwordx4 v[112:115], v[6:7], off
	v_lshl_add_u64 v[4:5], v[4:5], 0, s[2:3]
	global_load_dwordx4 v[116:119], v[4:5], off offset:32
	global_load_dwordx4 v[120:123], v[4:5], off offset:64
	global_load_dwordx4 v[124:127], v[4:5], off offset:96
	s_lshl_b32 s2, s6, 5
	s_lshl_b32 s3, s16, 3
	v_readlane_b32 s4, v255, 26
	s_add_i32 s2, s2, 0
	s_lshl_b32 s4, s4, 2
	s_add_i32 s2, s2, s3
	s_add_i32 s2, s2, s4
	s_add_i32 s2, s2, 0x24a00
	v_mov_b32_e32 v0, s2
	ds_read_b32 v3, v0
	s_waitcnt vmcnt(2)
	v_lshlrev_b32_e32 v11, 16, v116
	v_lshlrev_b32_e32 v0, 16, v112
	v_and_b32_e32 v4, 0xffff0000, v112
	v_fma_f32 v0, v0, v0, 0
	v_lshlrev_b32_e32 v5, 16, v113
	v_fmac_f32_e32 v0, v4, v4
	v_and_b32_e32 v6, 0xffff0000, v113
	v_fmac_f32_e32 v0, v5, v5
	v_lshlrev_b32_e32 v7, 16, v114
	v_fmac_f32_e32 v0, v6, v6
	v_and_b32_e32 v8, 0xffff0000, v114
	v_fmac_f32_e32 v0, v7, v7
	v_lshlrev_b32_e32 v9, 16, v115
	v_fmac_f32_e32 v0, v8, v8
	v_and_b32_e32 v10, 0xffff0000, v115
	v_fmac_f32_e32 v0, v9, v9
	v_fmac_f32_e32 v0, v10, v10
	v_and_b32_e32 v12, 0xffff0000, v116
	v_fmac_f32_e32 v0, v11, v11
	v_lshlrev_b32_e32 v13, 16, v117
	v_fmac_f32_e32 v0, v12, v12
	v_and_b32_e32 v14, 0xffff0000, v117
	v_fmac_f32_e32 v0, v13, v13
	v_lshlrev_b32_e32 v15, 16, v118
	v_fmac_f32_e32 v0, v14, v14
	v_and_b32_e32 v16, 0xffff0000, v118
	v_fmac_f32_e32 v0, v15, v15
	v_lshlrev_b32_e32 v17, 16, v119
	v_fmac_f32_e32 v0, v16, v16
	v_and_b32_e32 v18, 0xffff0000, v119
	v_fmac_f32_e32 v0, v17, v17
	s_waitcnt vmcnt(1)
	v_lshlrev_b32_e32 v19, 16, v120
	v_fmac_f32_e32 v0, v18, v18
	v_and_b32_e32 v20, 0xffff0000, v120
	v_fmac_f32_e32 v0, v19, v19
	v_lshlrev_b32_e32 v21, 16, v121
	v_fmac_f32_e32 v0, v20, v20
	v_and_b32_e32 v22, 0xffff0000, v121
	v_fmac_f32_e32 v0, v21, v21
	v_lshlrev_b32_e32 v23, 16, v122
	v_fmac_f32_e32 v0, v22, v22
	v_and_b32_e32 v24, 0xffff0000, v122
	v_fmac_f32_e32 v0, v23, v23
	v_lshlrev_b32_e32 v25, 16, v123
	v_fmac_f32_e32 v0, v24, v24
	v_and_b32_e32 v26, 0xffff0000, v123
	v_fmac_f32_e32 v0, v25, v25
	s_waitcnt vmcnt(0)
	v_lshlrev_b32_e32 v27, 16, v124
	v_fmac_f32_e32 v0, v26, v26
	v_and_b32_e32 v28, 0xffff0000, v124
	v_fmac_f32_e32 v0, v27, v27
	v_lshlrev_b32_e32 v29, 16, v125
	v_fmac_f32_e32 v0, v28, v28
	v_and_b32_e32 v30, 0xffff0000, v125
	v_fmac_f32_e32 v0, v29, v29
	v_lshlrev_b32_e32 v31, 16, v126
	v_fmac_f32_e32 v0, v30, v30
	v_and_b32_e32 v32, 0xffff0000, v126
	v_fmac_f32_e32 v0, v31, v31
	v_lshlrev_b32_e32 v33, 16, v127
	v_fmac_f32_e32 v0, v32, v32
	v_and_b32_e32 v34, 0xffff0000, v127
	v_fmac_f32_e32 v0, v33, v33
	v_fmac_f32_e32 v0, v34, v34
	v_mov_b32_e32 v4, v0
	s_nop 1
	v_permlane32_swap_b32_e32 v0, v4
	v_add_f32_e32 v0, v0, v4
	s_nop 1
	v_mov_b32_dpp v4, v0 row_shr:1 row_mask:0xf bank_mask:0xf bound_ctrl:1
	v_max_f32_e32 v4, v4, v4
	v_max_f32_e32 v0, v0, v4
	s_nop 1
	v_mov_b32_dpp v4, v0 row_shr:2 row_mask:0xf bank_mask:0xf bound_ctrl:1
	v_max_f32_e32 v4, v4, v4
	v_max_f32_e32 v0, v0, v4
	s_nop 1
	v_mov_b32_dpp v4, v0 row_shr:4 row_mask:0xf bank_mask:0xf bound_ctrl:1
	v_max_f32_e32 v4, v4, v4
	v_max_f32_e32 v0, v0, v4
	s_nop 1
	v_mov_b32_dpp v4, v0 row_shr:8 row_mask:0xf bank_mask:0xf bound_ctrl:1
	v_max_f32_e32 v4, v4, v4
	v_max_f32_e32 v0, v0, v4
	v_mov_b32_e32 v4, v0
	s_nop 1
	v_permlane16_swap_b32_e32 v0, v4
	v_max_f32_e32 v4, v4, v4
	v_max_f32_e32 v0, v0, v0
	v_max_f32_e32 v0, v0, v4
	s_nop 0
	v_readlane_b32 s2, v0, 15
	s_waitcnt lgkmcnt(0)
	s_nop 0
	v_mul_f32_e32 v0, s2, v3
	s_mov_b32 s2, 0xf800000
	v_mul_f32_e32 v4, 0x4f800000, v0
	v_cmp_gt_f32_e32 vcc, s2, v0
	s_nop 1
	v_cndmask_b32_e32 v4, v0, v4, vcc
	v_sqrt_f32_e32 v5, v4
	v_lshlrev_b32_e32 v0, 3, v216
	v_add_u32_e32 v6, -1, v5
	v_add_u32_e32 v7, 1, v5
	v_fma_f32 v8, -v6, v5, v4
	v_fma_f32 v9, -v7, v5, v4
	v_cmp_ge_f32_e64 s[4:5], 0, v8
	s_nop 1
	v_cndmask_b32_e64 v5, v5, v6, s[4:5]
	v_cmp_lt_f32_e64 s[4:5], 0, v9
	s_nop 1
	v_cndmask_b32_e64 v5, v5, v7, s[4:5]
	v_mul_f32_e32 v6, 0x37800000, v5
	v_cndmask_b32_e32 v5, v5, v6, vcc
	v_cmp_class_f32_e32 vcc, v4, v232
	s_nop 1
	v_cndmask_b32_e32 v4, v5, v4, vcc
	v_mul_f32_e32 v4, 0x3e38aa3b, v4
	v_cmp_lt_f32_e32 vcc, 0, v3
	v_mov_b32_e32 v3, 0x7f800000
	s_nop 0
	v_cndmask_b32_e32 v3, v3, v4, vcc
	v_cmp_gt_i32_e32 vcc, 2, v216
	v_readfirstlane_b32 s20, v3
	s_and_saveexec_b64 s[2:3], vcc
	v_add_u32_e32 v3, s68, v0
	ds_write_b8 v3, v1
	s_or_b64 exec, exec, s[2:3]
	v_ashrrev_i32_e32 v3, 3, v216
	v_readlane_b32 s2, v255, 11
	v_and_b32_e32 v8, 24, v0
	s_lshl_b32 s19, s10, 1
	v_add_u32_e32 v3, s2, v3
	v_readlane_b32 s2, v255, 12
	v_lshrrev_b32_e32 v4, 1, v3
	v_add_u32_e32 v2, s30, v2
	v_or_b32_e32 v9, s2, v8
	s_lshl_b32 s2, s16, 24
	v_lshrrev_b32_e32 v7, 2, v216
	v_lshlrev_b32_e32 v0, 1, v216
	v_lshlrev_b32_e32 v178, 2, v219
	s_lshl_b32 s23, s8, 1
	s_sub_i32 s4, -2.0, s2
	v_xor_b32_e32 v6, v4, v216
	v_and_or_b32 v4, v7, 7, v2
	v_lshlrev_b32_e32 v2, 7, v3
	v_and_b32_e32 v10, 32, v0
	v_and_or_b32 v0, v7, 3, v178
	s_add_u32 s2, s17, s19
	v_ashrrev_i32_e32 v3, 31, v2
	v_lshlrev_b32_e32 v7, 6, v0
	s_addc_u32 s3, s18, 0
	v_lshlrev_b32_e32 v0, 4, v6
	v_lshlrev_b32_e32 v4, 7, v4
	v_lshl_add_u64 v[2:3], v[2:3], 1, s[2:3]
	v_and_b32_e32 v0, 0x70, v0
	v_ashrrev_i32_e32 v5, 31, v4
	v_lshl_add_u64 v[2:3], v[2:3], 0, v[0:1]
	s_mov_b64 s[10:11], 0x5000000
	v_lshl_add_u64 v[180:181], v[2:3], 0, s[10:11]
	v_lshl_add_u64 v[2:3], v[4:5], 1, s[2:3]
	v_lshlrev_b32_e32 v0, 1, v9
	v_lshl_add_u64 v[2:3], v[2:3], 0, v[0:1]
	s_mov_b64 s[2:3], 0x6000000
	v_lshl_add_u64 v[182:183], v[2:3], 0, s[2:3]
	s_lshl_b32 s2, s8, 15
	s_lshr_b32 s21, s9, 6
	s_or_b32 s80, s2, 0x4000
	s_mov_b32 s3, s81
	v_readlane_b32 s8, v255, 13
	v_lshl_add_u64 v[200:201], v[180:181], 0, s[80:81]
	v_lshl_add_u64 v[194:195], v[182:183], 0, s[80:81]
	v_lshl_add_u64 v[190:191], v[180:181], 0, s[2:3]
	v_lshl_add_u64 v[184:185], v[182:183], 0, s[2:3]
	v_readlane_b32 s9, v255, 14
	v_or3_b32 v220, v7, v10, v8
	v_lshl_add_u64 v[198:199], v[200:201], 0, s[88:89]
	v_lshl_add_u64 v[192:193], v[194:195], 0, s[88:89]
	v_lshl_add_u64 v[188:189], v[190:191], 0, s[88:89]
	s_mov_b64 s[2:3], -1
	s_andn2_b64 vcc, exec, s[8:9]
	v_lshl_add_u64 v[186:187], v[184:185], 0, s[88:89]
	s_cbranch_vccnz .LBB0_424
	s_mov_b32 s2, m0
	s_mov_b32 m0, s76
	s_nop 0
	global_load_lds_dwordx4 v[200:201], off
	s_mov_b32 m0, s2
	v_readlane_b32 s3, v255, 15
	s_mov_b32 s2, m0
	s_mov_b32 m0, s3
	s_nop 0
	global_load_lds_dwordx4 v[198:199], off
	s_mov_b32 m0, s2
	v_readlane_b32 s3, v255, 16
	s_mov_b32 s2, m0
	s_mov_b32 m0, s31
	s_nop 0
	global_load_lds_dwordx4 v[194:195], off
	s_mov_b32 m0, s2
	s_cmp_eq_u32 s22, 15
	s_mov_b32 s2, m0
	s_mov_b32 m0, s3
	s_nop 0
	global_load_lds_dwordx4 v[192:193], off
	s_mov_b32 m0, s2
	v_readlane_b32 s3, v255, 17
	s_mov_b32 s2, m0
	s_mov_b32 m0, s3
	s_nop 0
	global_load_lds_dwordx4 v[190:191], off
	s_mov_b32 m0, s2
	v_readlane_b32 s3, v255, 18
	s_mov_b32 s2, m0
	s_mov_b32 m0, s3
	s_nop 0
	global_load_lds_dwordx4 v[188:189], off
	s_mov_b32 m0, s2
	v_readlane_b32 s3, v255, 19
	s_mov_b32 s2, m0
	s_mov_b32 m0, s3
	s_nop 0
	global_load_lds_dwordx4 v[184:185], off
	s_mov_b32 m0, s2
	v_readlane_b32 s3, v255, 20
	s_mov_b32 s2, m0
	s_mov_b32 m0, s3
	s_nop 0
	global_load_lds_dwordx4 v[186:187], off
	s_mov_b32 m0, s2
	s_cbranch_scc1 .LBB0_391
	s_add_i32 s80, s23, -1
	s_lshl_b64 s[2:3], s[80:81], 14
	v_lshl_add_u64 v[2:3], v[180:181], 0, s[2:3]
	v_readlane_b32 s8, v255, 21
	s_mov_b32 s5, m0
	s_mov_b32 m0, s8
	s_nop 0
	global_load_lds_dwordx4 v[2:3], off
	s_mov_b32 m0, s5
	v_lshl_add_u64 v[2:3], v[2:3], 0, s[88:89]
	v_readlane_b32 s8, v255, 22
	s_mov_b32 s5, m0
	s_mov_b32 m0, s8
	s_nop 0
	global_load_lds_dwordx4 v[2:3], off
	s_mov_b32 m0, s5
	v_lshl_add_u64 v[2:3], v[182:183], 0, s[2:3]
	v_readlane_b32 s3, v255, 23
	s_mov_b32 s2, m0
	s_mov_b32 m0, s3
	s_nop 0
	global_load_lds_dwordx4 v[2:3], off
	s_mov_b32 m0, s2
	v_lshl_add_u64 v[2:3], v[2:3], 0, s[88:89]
	v_readlane_b32 s3, v255, 24
	s_mov_b32 s2, m0
	s_mov_b32 m0, s3
	s_nop 0
	global_load_lds_dwordx4 v[2:3], off
	s_mov_b32 m0, s2
.LBB0_391:
	v_lshrrev_b32_e32 v0, 1, v216
	v_bitop3_b32 v2, v0, v219, 7 bitop3:0x6c
	v_lshlrev_b32_e32 v223, 4, v2
	v_add_u32_e32 v2, 2, v219
	v_bitop3_b32 v2, v2, v0, 7 bitop3:0x78
	v_lshlrev_b32_e32 v224, 4, v2
	v_add_u32_e32 v2, 4, v219
	v_bitop3_b32 v2, v2, v0, 7 bitop3:0x78
	v_lshlrev_b32_e32 v225, 4, v2
	v_add_u32_e32 v2, 6, v219
	v_bitop3_b32 v0, v2, v0, 7 bitop3:0x78
	s_add_i32 s2, 0, 0x10000
	v_lshlrev_b32_e32 v233, 4, v0
	v_mov_b32_e32 v0, 0x3e38aa3b
	v_mov_b32_e32 v14, v1
	v_mov_b32_e32 v15, v1
	v_mov_b64_e32 v[130:131], v[118:119]
	v_mov_b64_e32 v[134:135], v[126:127]
	v_mov_b64_e32 v[138:139], v[114:115]
	v_mov_b64_e32 v[142:143], v[122:123]
	v_add_u32_e32 v221, s2, v220
	s_xor_b32 s2, s4, 0x80000000
	v_mul_f32_e32 v234, s4, v0
	v_readlane_b32 s8, v255, 30
	v_mov_b32_e32 v0, v1
	v_mov_b32_e32 v2, v1
	v_mov_b32_e32 v3, v1
	v_mov_b32_e32 v4, v1
	v_mov_b32_e32 v5, v1
	v_mov_b32_e32 v6, v1
	v_mov_b32_e32 v7, v1
	v_mov_b32_e32 v8, v1
	v_mov_b32_e32 v9, v1
	v_mov_b32_e32 v10, v1
	v_mov_b32_e32 v11, v1
	v_mov_b32_e32 v12, v1
	v_mov_b32_e32 v13, v1
	v_mov_b64_e32 v[30:31], v[14:15]
	v_mov_b64_e32 v[46:47], v[14:15]
	v_mov_b64_e32 v[62:63], v[14:15]
	v_mov_b64_e32 v[78:79], v[14:15]
	v_mov_b64_e32 v[128:129], v[116:117]
	v_mov_b64_e32 v[132:133], v[124:125]
	v_mov_b64_e32 v[136:137], v[112:113]
	v_mov_b64_e32 v[140:141], v[120:121]
	v_lshlrev_b32_e32 v222, 7, v218
	s_mov_b32 s5, s4
	s_mov_b32 s3, s2
	s_mov_b32 s24, 0
	v_sub_u32_e32 v235, 0, v178
	v_add_u32_e32 v236, s8, v218
	s_sub_i32 s25, 1, s21
	s_add_i32 s80, s23, -2
	s_mov_b64 s[10:11], 0
	v_mov_b32_e32 v217, 0
	v_mov_b32_e32 v237, 0xff800000
	s_mov_b32 s26, 8
	s_mov_b32 s27, 0xc000
	v_mov_b64_e32 v[28:29], v[12:13]
	v_mov_b64_e32 v[26:27], v[10:11]
	v_mov_b64_e32 v[24:25], v[8:9]
	v_mov_b64_e32 v[22:23], v[6:7]
	v_mov_b64_e32 v[20:21], v[4:5]
	v_mov_b64_e32 v[18:19], v[2:3]
	v_mov_b64_e32 v[16:17], v[0:1]
	v_mov_b64_e32 v[44:45], v[12:13]
	v_mov_b64_e32 v[42:43], v[10:11]
	v_mov_b64_e32 v[40:41], v[8:9]
	v_mov_b64_e32 v[38:39], v[6:7]
	v_mov_b64_e32 v[36:37], v[4:5]
	v_mov_b64_e32 v[34:35], v[2:3]
	v_mov_b64_e32 v[32:33], v[0:1]
	v_mov_b64_e32 v[60:61], v[12:13]
	v_mov_b64_e32 v[58:59], v[10:11]
	v_mov_b64_e32 v[56:57], v[8:9]
	v_mov_b64_e32 v[54:55], v[6:7]
	v_mov_b64_e32 v[52:53], v[4:5]
	v_mov_b64_e32 v[50:51], v[2:3]
	v_mov_b64_e32 v[48:49], v[0:1]
	v_mov_b64_e32 v[76:77], v[12:13]
	v_mov_b64_e32 v[74:75], v[10:11]
	v_mov_b64_e32 v[72:73], v[8:9]
	v_mov_b64_e32 v[70:71], v[6:7]
	v_mov_b64_e32 v[68:69], v[4:5]
	v_mov_b64_e32 v[66:67], v[2:3]
	v_mov_b64_e32 v[64:65], v[0:1]
	s_branch .LBB0_393
.Ldl_tf:
	s_mov_b32 s97, s96
	s_waitcnt lgkmcnt(0)
	v_cmp_eq_u64_e64 s[8:9], s[96:97], v[14:15]
	s_and_b64 vcc, exec, s[8:9]
	s_cbranch_vccnz .LBB0_420
	s_cmp_lt_i32 s80, 0
	s_cbranch_scc1 .Ldfst_l2
	s_and_b32 s92, s27, 0xc000
	s_cmp_gt_i32 s24, 1
	s_cselect_b32 s93, -2, 3
	s_add_i32 s93, s93, s24
	s_lshl_b32 s93, s93, 14
	s_lshl_b64 s[90:91], s[80:81], 14
	v_lshl_add_u64 v[80:81], v[180:181], 0, s[90:91]
	s_add_i32 s92, s76, s92
	s_mov_b32 m0, s92
	s_nop 0
	global_load_lds_dwordx4 v[80:81], off
	v_lshl_add_u64 v[80:81], v[80:81], 0, s[88:89]
	s_addk_i32 s92, 0x2000
	s_mov_b32 m0, s92
	s_nop 0
	global_load_lds_dwordx4 v[80:81], off
	v_lshl_add_u64 v[80:81], v[182:183], 0, s[90:91]
	s_add_i32 s92, s31, s93
	s_mov_b32 m0, s92
	s_nop 0
	global_load_lds_dwordx4 v[80:81], off
	v_lshl_add_u64 v[80:81], v[80:81], 0, s[88:89]
	s_addk_i32 s92, 0x2000
	s_mov_b32 m0, s92
	s_nop 0
	global_load_lds_dwordx4 v[80:81], off
.Ldfst_l2:
	s_branch .Ldl_join

.LBB0_402:
	s_and_b32 s8, s26, 8
	s_add_i32 s8, s8, 0
	s_add_i32 s8, s8, 0x241c0
	v_mov_b32_e32 v0, s8
	ds_read_b64 v[14:15], v0
	s_cmp_lg_u32 s29, 0
	s_cbranch_scc1 .Ldl_tf
	s_cmp_lt_i32 s12, 3
	s_cbranch_scc1 .LBB0_404
	s_and_b32 s13, s27, 0xc000
	s_cmp_gt_i32 s24, 1
	s_cselect_b32 s8, -2, 3
	s_add_i32 s8, s8, s24
	s_lshl_b32 s14, s8, 14
	s_lshl_b64 s[8:9], s[80:81], 14
	v_lshl_add_u64 v[80:81], v[180:181], 0, s[8:9]
	s_add_i32 s13, s76, s13
	s_mov_b32 s15, m0
	s_mov_b32 m0, s13
	s_nop 0
	global_load_lds_dwordx4 v[80:81], off
	s_mov_b32 m0, s15
	v_lshl_add_u64 v[80:81], v[80:81], 0, s[88:89]
	s_addk_i32 s13, 0x2000
	s_mov_b32 s15, m0
	s_mov_b32 m0, s13
	s_nop 0
	global_load_lds_dwordx4 v[80:81], off
	s_mov_b32 m0, s15
	v_lshl_add_u64 v[80:81], v[182:183], 0, s[8:9]
	s_add_i32 s8, s31, s14
	s_mov_b32 s9, m0
	s_mov_b32 m0, s8
	s_nop 0
	global_load_lds_dwordx4 v[80:81], off
	s_mov_b32 m0, s9
	v_lshl_add_u64 v[80:81], v[80:81], 0, s[88:89]
	s_addk_i32 s8, 0x2000
	s_mov_b32 s9, m0
	s_mov_b32 m0, s8
	s_nop 0
	global_load_lds_dwordx4 v[80:81], off
	s_mov_b32 m0, s9
.LBB0_404:
	s_mov_b32 s97, s96
	s_waitcnt lgkmcnt(0)
	v_cmp_eq_u64_e64 s[8:9], s[96:97], v[14:15]
	s_and_b64 vcc, exec, s[8:9]
	s_cbranch_vccnz .LBB0_420
.Ldl_join:
	s_cmp_gt_i32 s12, s21
	s_cbranch_scc1 .LBB0_417
	s_xor_b64 s[12:13], s[10:11], -1
	s_add_i32 s10, s27, 0xffff4000
	s_and_b32 s10, s10, 0xc000
	s_add_i32 s14, s34, s10
	v_add_u32_e32 v0, s14, v222
	s_mov_b64 s[10:11], -1
	s_and_b64 vcc, exec, s[12:13]
	v_add_u32_e32 v202, v0, v223
	v_add_u32_e32 v15, v0, v224
	v_add_u32_e32 v14, v0, v225
	v_add_u32_e32 v0, v0, v233
	s_cbranch_vccz .LBB0_408
	ds_read_b128 v[80:83], v202
	ds_read_b128 v[84:87], v202 offset:4096
	ds_read_b128 v[148:151], v15
	ds_read_b128 v[204:207], v15 offset:4096
	ds_read_b128 v[208:211], v14
	ds_read_b128 v[212:215], v14 offset:4096
	ds_read_b128 v[238:241], v0
	ds_read_b128 v[242:245], v0 offset:4096
	s_waitcnt lgkmcnt(7)
	v_mfma_f32_32x32x16_bf16 v[96:111], v[80:83], v[136:139], 0
	s_mov_b64 s[10:11], 0
	s_waitcnt lgkmcnt(6)
	v_mfma_f32_32x32x16_bf16 v[80:95], v[84:87], v[136:139], 0
	s_waitcnt lgkmcnt(5)
	v_mfma_f32_32x32x16_bf16 v[96:111], v[148:151], v[128:131], v[96:111]
	s_waitcnt lgkmcnt(4)
	v_mfma_f32_32x32x16_bf16 v[80:95], v[204:207], v[128:131], v[80:95]
	s_waitcnt lgkmcnt(3)
	v_mfma_f32_32x32x16_bf16 v[96:111], v[208:211], v[140:143], v[96:111]
	s_waitcnt lgkmcnt(2)
	v_mfma_f32_32x32x16_bf16 v[80:95], v[212:215], v[140:143], v[80:95]
	s_waitcnt lgkmcnt(1)
	v_mfma_f32_32x32x16_bf16 v[96:111], v[238:241], v[132:135], v[96:111]
	s_waitcnt lgkmcnt(0)
	v_mfma_f32_32x32x16_bf16 v[80:95], v[242:245], v[132:135], v[80:95]

.LBB0_417:
	v_add_u32_e32 v0, 1, v236
	v_cvt_f32_i32_e32 v0, v0
	s_mov_b64 s[12:13], exec
	v_fma_f32 v0, v234, v0, s20
	v_sub_f32_e32 v0, v0, v237
	v_cmp_gt_f32_e32 vcc, s52, v0
	s_and_saveexec_b64 s[14:15], s[86:87]
	s_cbranch_execz .LBB0_419
	s_add_i32 s28, s26, -8
	s_and_b32 s28, s28, 8
	s_add_i32 s28, s68, s28
	s_cmp_eq_u64 vcc, s[12:13]
	s_cselect_b64 s[12:13], -1, 0
	s_mov_b32 s29, s12
	v_cndmask_b32_e64 v0, 0, 1, s[12:13]
	v_mov_b32_e32 v14, s28
	ds_write_b8 v14, v0

.LBB0_435:
	s_add_i32 s23, s22, 8
	s_and_b32 s8, s23, 8
	s_add_i32 s8, s8, 0
	s_add_i32 s8, s8, 0x241c0
	v_mov_b32_e32 v0, s8
	ds_read_b64 v[2:3], v0
	s_cmp_lg_u32 s29, 0
	s_cbranch_scc1 .Lde_tf
	s_cmp_lt_i32 s15, 3
	s_cbranch_scc1 .LBB0_437
	s_and_b32 s11, s13, 0xc000
	s_cmp_gt_i32 s14, 1
	s_cselect_b32 s8, -2, 3
	s_add_i32 s8, s8, s14
	s_add_i32 s80, s10, -4
	s_lshl_b32 s24, s8, 14
	s_lshl_b64 s[8:9], s[80:81], 14
	v_lshl_add_u64 v[4:5], v[180:181], 0, s[8:9]
	s_add_i32 s11, s76, s11
	s_mov_b32 s25, m0
	s_mov_b32 m0, s11
	s_nop 0
	global_load_lds_dwordx4 v[4:5], off
	s_mov_b32 m0, s25
	v_lshl_add_u64 v[4:5], v[4:5], 0, s[88:89]
	s_addk_i32 s11, 0x2000
	s_mov_b32 s25, m0
	s_mov_b32 m0, s11
	s_nop 0
	global_load_lds_dwordx4 v[4:5], off
	s_mov_b32 m0, s25
	v_lshl_add_u64 v[4:5], v[182:183], 0, s[8:9]
	s_add_i32 s8, s31, s24
	s_mov_b32 s9, m0
	s_mov_b32 m0, s8
	s_nop 0
	global_load_lds_dwordx4 v[4:5], off
	s_mov_b32 m0, s9
	v_lshl_add_u64 v[4:5], v[4:5], 0, s[88:89]
	s_addk_i32 s8, 0x2000
	s_mov_b32 s9, m0
	s_mov_b32 m0, s8
	s_nop 0
	global_load_lds_dwordx4 v[4:5], off
	s_mov_b32 m0, s9
.LBB0_437:
	s_mov_b32 s97, s96
	s_waitcnt lgkmcnt(0)
	v_cmp_eq_u64_e64 s[8:9], s[96:97], v[2:3]
	s_and_b64 vcc, exec, s[8:9]
	s_cbranch_vccnz .LBB0_449
.Lde_join:
	s_cmp_gt_i32 s15, s21
	s_cbranch_scc1 .LBB0_446
	s_add_i32 s8, s13, 0xffff4000
	s_and_b32 s8, s8, 0xc000
	v_add_u32_e32 v0, s8, v221
	v_add_u32_e32 v6, v0, v222
	v_add_u32_e32 v14, v0, v223
	ds_read_b128 v[2:5], v6
	ds_read_b128 v[6:9], v6 offset:4096
	ds_read_b128 v[10:13], v14
	ds_read_b128 v[128:131], v14 offset:4096
	v_add_u32_e32 v14, v0, v224
	v_add_u32_e32 v0, v0, v219
	ds_read_b128 v[132:135], v14
	ds_read_b128 v[136:139], v14 offset:4096
	ds_read_b128 v[144:147], v0
	ds_read_b128 v[148:151], v0 offset:4096
	s_add_i32 s8, s12, s10
	s_lshl_b32 s9, s14, 14
	s_waitcnt lgkmcnt(7)
	v_mfma_f32_32x32x16_bf16 v[96:111], v[2:5], v[112:115], 0
	v_add_u32_e32 v235, s9, v220
	s_waitcnt lgkmcnt(6)
	v_mfma_f32_32x32x16_bf16 v[80:95], v[6:9], v[112:115], 0
	s_waitcnt lgkmcnt(5)
	v_mfma_f32_32x32x16_bf16 v[96:111], v[10:13], v[116:119], v[96:111]
	s_waitcnt lgkmcnt(4)
	v_mfma_f32_32x32x16_bf16 v[80:95], v[128:131], v[116:119], v[80:95]
	ds_read_b64_tr_b16 v[6:7], v235
	ds_read_b64_tr_b16 v[8:9], v235 offset:512
	ds_read_b64_tr_b16 v[2:3], v235 offset:1024
	ds_read_b64_tr_b16 v[4:5], v235 offset:1536
	ds_read_b64_tr_b16 v[140:141], v235 offset:4096
	ds_read_b64_tr_b16 v[142:143], v235 offset:4608
	ds_read_b64_tr_b16 v[128:129], v235 offset:5120
	ds_read_b64_tr_b16 v[130:131], v235 offset:5632
	s_waitcnt lgkmcnt(11)
	v_mfma_f32_32x32x16_bf16 v[96:111], v[132:135], v[120:123], v[96:111]
	s_waitcnt lgkmcnt(10)
	v_mfma_f32_32x32x16_bf16 v[80:95], v[136:139], v[120:123], v[80:95]
	s_waitcnt lgkmcnt(9)
	v_mfma_f32_32x32x16_bf16 v[96:111], v[144:147], v[124:127], v[96:111]
	ds_read_b64_tr_b16 v[136:137], v235 offset:2048
	ds_read_b64_tr_b16 v[138:139], v235 offset:2560
	ds_read_b64_tr_b16 v[10:11], v235 offset:3072
	ds_read_b64_tr_b16 v[12:13], v235 offset:3584
	ds_read_b64_tr_b16 v[144:145], v235 offset:6144
	ds_read_b64_tr_b16 v[146:147], v235 offset:6656
	ds_read_b64_tr_b16 v[132:133], v235 offset:7168
	ds_read_b64_tr_b16 v[134:135], v235 offset:7680
	s_waitcnt lgkmcnt(14)
	v_mfma_f32_32x32x16_bf16 v[80:95], v[148:151], v[124:127], v[80:95]
	v_add_u32_e32 v0, v233, v218
	v_cvt_f32_i32_e32 v0, v0
	s_cmp_lg_u32 s8, 1
	s_mov_b64 s[8:9], -1
	s_cbranch_scc0 .LBB0_441
	v_add_f32_e32 v14, 0, v96
	v_subrev_f32_e32 v15, s4, v97
	s_nop 4
	v_fma_f32 v186, s2, v196, v80
	v_fma_f32 v187, s3, v197, v81
	v_fma_f32 v184, s2, v226, v98
	v_fma_f32 v185, s3, v227, v99
	v_max_f32_e32 v148, v14, v186
	v_max_f32_e32 v149, v15, v187
	v_fma_f32 v188, s2, v152, v82
	v_fma_f32 v189, s3, v153, v83
	v_max3_f32 v148, v148, s82, v149
	v_max_f32_e32 v149, v184, v188
	v_max_f32_e32 v150, v185, v189
	v_fma_f32 v190, s2, v154, v100
	v_fma_f32 v191, s3, v155, v101
	v_fma_f32 v192, s2, v156, v84
	v_fma_f32 v193, s3, v157, v85
	v_max3_f32 v148, v148, v149, v150
	v_max_f32_e32 v149, v190, v192
	v_max_f32_e32 v150, v191, v193
	v_fma_f32 v194, s2, v158, v102
	v_fma_f32 v195, s3, v159, v103
	v_fma_f32 v198, s2, v160, v86
	v_fma_f32 v199, s3, v161, v87
	v_max3_f32 v148, v148, v149, v150
	v_max_f32_e32 v149, v194, v198
	v_max_f32_e32 v150, v195, v199
	v_fma_f32 v200, s2, v162, v104
	v_fma_f32 v201, s3, v163, v105
	v_fma_f32 v202, s2, v164, v88
	v_fma_f32 v203, s3, v165, v89
	v_max3_f32 v148, v148, v149, v150
	v_max_f32_e32 v149, v200, v202
	v_max_f32_e32 v150, v201, v203
	v_fma_f32 v204, s2, v166, v106
	v_fma_f32 v205, s3, v167, v107
	v_fma_f32 v206, s2, v168, v90
	v_fma_f32 v207, s3, v169, v91
	v_max3_f32 v148, v148, v149, v150
	v_max_f32_e32 v149, v204, v206
	v_max_f32_e32 v150, v205, v207
	v_fma_f32 v208, s2, v170, v108
	v_fma_f32 v209, s3, v171, v109
	v_fma_f32 v210, s2, v172, v92
	v_fma_f32 v211, s3, v173, v93
	v_max3_f32 v148, v148, v149, v150
	v_max_f32_e32 v149, v208, v210
	v_max_f32_e32 v150, v209, v211
	v_fma_f32 v212, s2, v174, v110
	v_fma_f32 v213, s3, v175, v111
	v_fma_f32 v214, s2, v176, v94
	v_fma_f32 v215, s3, v177, v95
	v_max3_f32 v148, v148, v149, v150
	v_max_f32_e32 v149, v212, v214
	v_max_f32_e32 v150, v213, v215
	v_max3_f32 v237, v148, v149, v150
	v_mul_f32_e32 v236, s4, v0
	s_mov_b64 s[8:9], 0

.LBB0_446:
	v_add_u32_e32 v0, 1, v218
	v_cvt_f32_i32_e32 v0, v0
	s_mov_b64 s[8:9], exec
	v_fma_f32 v0, v225, v0, s20
	v_sub_f32_e32 v0, v0, v234
	v_cmp_gt_f32_e32 vcc, s52, v0
	s_and_saveexec_b64 s[10:11], s[86:87]
	s_cbranch_execz .LBB0_448
	s_and_b32 s22, s22, 8
	s_add_i32 s22, s68, s22
	s_cmp_eq_u64 vcc, s[8:9]
	s_cselect_b64 s[8:9], -1, 0
	s_mov_b32 s29, s8
	v_cndmask_b32_e64 v0, 0, 1, s[8:9]
	v_mov_b32_e32 v2, s22
	ds_write_b8 v2, v0

.Lde_tf:
	s_mov_b32 s97, s96
	s_waitcnt lgkmcnt(0)
	v_cmp_eq_u64_e64 s[8:9], s[96:97], v[2:3]
	s_and_b64 vcc, exec, s[8:9]
	s_cbranch_vccnz .LBB0_449
	s_cmp_lt_i32 s15, 3
	s_cbranch_scc1 .Ldfst_e2
	s_and_b32 s92, s13, 0xc000
	s_cmp_gt_i32 s14, 1
	s_cselect_b32 s93, -2, 3
	s_add_i32 s93, s93, s14
	s_add_i32 s80, s10, -4
	s_lshl_b32 s93, s93, 14
	s_lshl_b64 s[90:91], s[80:81], 14
	v_lshl_add_u64 v[4:5], v[180:181], 0, s[90:91]
	s_add_i32 s92, s76, s92
	s_mov_b32 m0, s92
	s_nop 0
	global_load_lds_dwordx4 v[4:5], off
	v_lshl_add_u64 v[4:5], v[4:5], 0, s[88:89]
	s_addk_i32 s92, 0x2000
	s_mov_b32 m0, s92
	s_nop 0
	global_load_lds_dwordx4 v[4:5], off
	v_lshl_add_u64 v[4:5], v[182:183], 0, s[90:91]
	s_add_i32 s92, s31, s93
	s_mov_b32 m0, s92
	s_nop 0
	global_load_lds_dwordx4 v[4:5], off
	v_lshl_add_u64 v[4:5], v[4:5], 0, s[88:89]
	s_addk_i32 s92, 0x2000
	s_mov_b32 m0, s92
	s_nop 0
	global_load_lds_dwordx4 v[4:5], off
